# P0 RMSNorm(x): gain vector loaded once before the loop (16 serialized store+reload round trips per iteration removed)
# speedup vs baseline: 1.0037x; 1.0037x over previous
; #define GAS __attribute__((address_space(1)))
; template <class T_> __device__ __forceinline__ T_* as_global(T_* p) { return (T_*)(GAS T_*)p; }
; __device__ __forceinline__ void rms_rows4_to_bf16(const float* xrow, const float* g, bf16* orow, int lane) {
;     const GAS f32x4* xr = (const GAS f32x4*)xrow + lane; const GAS f32x4* gr = (const GAS f32x4*)g + lane;
;     f32x4 v[4][4]; float s[4] = {0.f, 0.f, 0.f, 0.f};
; #pragma unroll
;     for (int r = 0; r < 4; ++r)
; #pragma unroll
;         for (int j = 0; j < 4; ++j) v[r][j] = xr[r * (D / 4) + 64 * j];
; #pragma unroll
;     for (int r = 0; r < 4; ++r)
; #pragma unroll
;         for (int j = 0; j < 4; ++j) s[r] += (v[r][j].x * v[r][j].x + v[r][j].y * v[r][j].y) + (v[r][j].z * v[r][j].z + v[r][j].w * v[r][j].w);
; __global__ void __launch_bounds__(NWAVES * 64, 2) hybrid_fwd(Args args) {
;     ...
;         { const float* xg0 = as_global(args->x); const float* gp0 = as_global(args->g_pre);
;           for (int m = 4 * gw; m < MTOK; m += 4 * NGW) rms_rows4_to_bf16(xg0 + (size_t)m * D, gp0, XN + (size_t)m * D, lane); }
.Lp0_rms:
	s_cmpk_gt_i32 s14, 0x3fff
	v_lshlrev_b32_e32 v70, 4, v7
	v_lshlrev_b32_e32 v1, 2, v7
	v_lshlrev_b32_e32 v72, 3, v7
	s_cbranch_scc1 .LBB0_60
	s_load_dwordx2 s[2:3], s[20:21], 0x10
	s_load_dwordx2 s[4:5], s[20:21], 0x0
	v_mov_b32_e32 v71, 0
	s_lshl_b32 s22, s14, 2
	s_ashr_i32 s23, s22, 31
	s_waitcnt lgkmcnt(0)
	v_lshl_add_u64 v[74:75], s[2:3], 0, v[70:71]
	global_load_dwordx4 v[112:115], v[74:75], off
	global_load_dwordx4 v[116:119], v[74:75], off offset:1024
	global_load_dwordx4 v[120:123], v[74:75], off offset:2048
	global_load_dwordx4 v[124:127], v[74:75], off offset:3072
	s_load_dword s2, s[0:1], 0xa8
	v_mov_b32_e32 v73, v71
	v_xor_b32_e32 v82, 4, v1
	v_xor_b32_e32 v83, 8, v1
	v_xor_b32_e32 v84, 16, v1
	s_waitcnt lgkmcnt(0)
	s_lshl_b32 s24, s2, 5
	s_lshl_b64 s[2:3], s[22:23], 12
	s_add_u32 s2, s4, s2
	s_addc_u32 s3, s5, s3
	s_ashr_i32 s25, s24, 31
	v_lshl_add_u64 v[76:77], s[2:3], 0, v[70:71]
	s_lshl_b64 s[26:27], s[24:25], 12
	s_lshl_b64 s[2:3], s[22:23], 11
	s_add_u32 s2, s18, s2
	s_addc_u32 s3, s19, s3
	v_lshl_add_u64 v[2:3], s[2:3], 0, v[72:73]
	s_mov_b64 s[2:3], 0x3c00000
	v_xor_b32_e32 v85, 32, v1
	v_xor_b32_e32 v86, 64, v1
	v_xor_b32_e32 v87, 0x80, v1
	v_lshl_add_u64 v[78:79], v[2:3], 0, s[2:3]
	s_lshl_b64 s[28:29], s[24:25], 11
	s_movk_i32 s2, 0x1000
	v_mov_b32_e32 v71, 0x358637bd
	s_mov_b32 s3, 0xf800000
	v_mov_b32_e32 v73, 0x260
	s_movk_i32 s13, 0x7fff
	s_mov_b32 s15, 0xffff0000
	s_waitcnt vmcnt(0)
.LBB0_59:
	global_load_dwordx4 v[14:17], v[76:77], off
	global_load_dwordx4 v[10:13], v[76:77], off offset:1024
	global_load_dwordx4 v[6:9], v[76:77], off offset:2048
	global_load_dwordx4 v[2:5], v[76:77], off offset:3072
	v_add_co_u32_e32 v22, vcc, 0x1000, v76
	v_mov_b32_e32 v18, v112
	v_mov_b32_e32 v19, v113
	v_mov_b32_e32 v20, v114
	v_mov_b32_e32 v21, v115
	s_nop 0
	v_addc_co_u32_e32 v23, vcc, 0, v77, vcc
	v_add_co_u32_e32 v24, vcc, 0x2000, v76
	global_load_dwordx4 v[66:69], v[22:23], off
	global_load_dwordx4 v[62:65], v[22:23], off offset:1024
	global_load_dwordx4 v[58:61], v[22:23], off offset:2048
	global_load_dwordx4 v[54:57], v[22:23], off offset:3072
	v_addc_co_u32_e32 v25, vcc, 0, v77, vcc
	global_load_dwordx4 v[50:53], v[24:25], off
	global_load_dwordx4 v[46:49], v[24:25], off offset:1024
	global_load_dwordx4 v[42:45], v[24:25], off offset:2048
	global_load_dwordx4 v[38:41], v[24:25], off offset:3072
	v_add_co_u32_e32 v88, vcc, 0x3000, v76
	v_add_co_u32_e64 v80, s[4:5], s2, v78
	s_nop 0
	v_addc_co_u32_e32 v89, vcc, 0, v77, vcc
	global_load_dwordx4 v[34:37], v[88:89], off
	global_load_dwordx4 v[30:33], v[88:89], off offset:1024
	global_load_dwordx4 v[26:29], v[88:89], off offset:2048
	global_load_dwordx4 v[22:25], v[88:89], off offset:3072
	v_addc_co_u32_e64 v81, s[4:5], 0, v79, s[4:5]
	s_add_i32 s22, s22, s24
	s_cmp_gt_i32 s22, 0xffff
	v_lshl_add_u64 v[76:77], v[76:77], 0, s[26:27]
	s_waitcnt vmcnt(15)
	v_mul_f32_e32 v88, v15, v15
	v_mul_f32_e32 v89, v17, v17
	s_waitcnt vmcnt(14)
	v_mul_f32_e32 v90, v11, v11
	v_mul_f32_e32 v91, v13, v13
	s_waitcnt vmcnt(13)
	v_mul_f32_e32 v92, v7, v7
	v_mul_f32_e32 v93, v9, v9
	s_waitcnt vmcnt(12)
	v_mul_f32_e32 v94, v3, v3
	v_mul_f32_e32 v95, v5, v5
	v_fmac_f32_e32 v88, v14, v14
	v_fmac_f32_e32 v89, v16, v16
	v_fmac_f32_e32 v90, v10, v10
	v_fmac_f32_e32 v91, v12, v12
	v_fmac_f32_e32 v92, v6, v6
	v_fmac_f32_e32 v93, v8, v8
	v_fmac_f32_e32 v94, v2, v2
	v_fmac_f32_e32 v95, v4, v4
	v_add_f32_e32 v88, v88, v89
	v_add_f32_e32 v89, v90, v91
	v_add_f32_e32 v90, v92, v93
	v_add_f32_e32 v91, v94, v95
	s_waitcnt vmcnt(11)
	v_mul_f32_e32 v92, v67, v67
	v_mul_f32_e32 v93, v69, v69
	s_waitcnt vmcnt(10)
	v_mul_f32_e32 v94, v63, v63
	v_mul_f32_e32 v95, v65, v65
	v_add_f32_e32 v88, v88, v89
	s_waitcnt vmcnt(9)
	v_mul_f32_e32 v96, v59, v59
	v_mul_f32_e32 v97, v61, v61
	v_fmac_f32_e32 v92, v66, v66
	v_fmac_f32_e32 v93, v68, v68
	v_fmac_f32_e32 v94, v62, v62
	v_fmac_f32_e32 v95, v64, v64
	s_waitcnt vmcnt(6)
	v_mul_f32_e32 v101, v47, v47
	v_mul_f32_e32 v102, v49, v49
	v_add_f32_e32 v88, v88, v90
	v_mul_f32_e32 v98, v55, v55
	v_mul_f32_e32 v99, v57, v57
	v_fmac_f32_e32 v96, v58, v58
	v_fmac_f32_e32 v97, v60, v60
	v_mul_f32_e32 v89, v51, v51
	v_mul_f32_e32 v100, v53, v53
	v_add_f32_e32 v90, v92, v93
	v_add_f32_e32 v92, v94, v95
	v_fmac_f32_e32 v101, v46, v46
	v_fmac_f32_e32 v102, v48, v48
	v_add_f32_e32 v88, v88, v91
	v_fmac_f32_e32 v98, v54, v54
	v_fmac_f32_e32 v99, v56, v56
	s_waitcnt vmcnt(5)
	v_mul_f32_e32 v103, v43, v43
	v_mul_f32_e32 v104, v45, v45
	v_add_f32_e32 v93, v96, v97
	v_fmac_f32_e32 v89, v50, v50
	v_fmac_f32_e32 v100, v52, v52
	v_add_f32_e32 v90, v90, v92
	v_add_f32_e32 v91, v101, v102
	ds_bpermute_b32 v101, v82, v88
	s_waitcnt vmcnt(4)
	v_mul_f32_e32 v105, v39, v39
	v_mul_f32_e32 v106, v41, v41
	v_add_f32_e32 v94, v98, v99
	v_fmac_f32_e32 v103, v42, v42
	v_fmac_f32_e32 v104, v44, v44
	s_waitcnt vmcnt(3)
	v_mul_f32_e32 v95, v35, v35
	v_mul_f32_e32 v96, v37, v37
	s_waitcnt vmcnt(2)
	v_mul_f32_e32 v97, v31, v31
	v_mul_f32_e32 v98, v33, v33
	v_add_f32_e32 v89, v89, v100
	v_add_f32_e32 v90, v90, v93
	v_fmac_f32_e32 v105, v38, v38
	v_fmac_f32_e32 v106, v40, v40
	s_waitcnt vmcnt(1)
	v_mul_f32_e32 v99, v27, v27
	v_mul_f32_e32 v107, v29, v29
	v_add_f32_e32 v92, v103, v104
	v_fmac_f32_e32 v95, v34, v34
	v_fmac_f32_e32 v96, v36, v36
	v_fmac_f32_e32 v97, v30, v30
	v_fmac_f32_e32 v98, v32, v32
	v_add_f32_e32 v89, v89, v91
	v_add_f32_e32 v90, v90, v94
	s_waitcnt vmcnt(0)
; __device__ __forceinline__ float wave_sum(float v, int lane) {
; #pragma unroll
;     for (int o = 1; o < 64; o <<= 1) v += __builtin_bit_cast(float, __builtin_amdgcn_ds_bpermute((lane ^ o) << 2, __builtin_bit_cast(int, v)));
;     return v;
; __device__ __forceinline__ void rms_rows4_to_bf16(const float* xrow, const float* g, bf16* orow, int lane) {
;     ...
; #pragma unroll
;     for (int r = 0; r < 4; ++r)
; #pragma unroll
;         for (int j = 0; j < 4; ++j) s[r] += (v[r][j].x * v[r][j].x + v[r][j].y * v[r][j].y) + (v[r][j].z * v[r][j].z + v[r][j].w * v[r][j].w);
; #pragma unroll
;     for (int r = 0; r < 4; ++r) { const float rs = 1.f / sqrtf(wave_sum(s[r], lane) * (1.f / D) + RMS_EPS);
	v_mul_f32_e32 v108, v23, v23
	v_mul_f32_e32 v109, v25, v25
	v_add_f32_e32 v100, v105, v106
	v_fmac_f32_e32 v99, v26, v26
	v_fmac_f32_e32 v107, v28, v28
	v_add_f32_e32 v91, v95, v96
	v_add_f32_e32 v93, v97, v98
	v_add_f32_e32 v89, v89, v92
	ds_bpermute_b32 v92, v82, v90
	v_fmac_f32_e32 v108, v22, v22
	v_fmac_f32_e32 v109, v24, v24
	v_add_f32_e32 v95, v99, v107
	v_add_f32_e32 v91, v91, v93
	v_add_f32_e32 v89, v89, v100
	v_add_f32_e32 v96, v108, v109
	v_add_f32_e32 v91, v91, v95
	ds_bpermute_b32 v93, v82, v89
	s_waitcnt lgkmcnt(2)
	v_add_f32_e32 v88, v88, v101
	v_add_f32_e32 v91, v91, v96
	ds_bpermute_b32 v95, v83, v88
	ds_bpermute_b32 v94, v82, v91
	s_waitcnt lgkmcnt(3)
	v_add_f32_e32 v90, v90, v92
	ds_bpermute_b32 v92, v83, v90
	s_waitcnt lgkmcnt(3)
	v_add_f32_e32 v89, v89, v93
	ds_bpermute_b32 v93, v83, v89
	s_waitcnt lgkmcnt(3)
	v_add_f32_e32 v88, v88, v95
	s_waitcnt lgkmcnt(2)
	v_add_f32_e32 v91, v91, v94
	ds_bpermute_b32 v94, v84, v88
	s_waitcnt lgkmcnt(2)
	v_add_f32_e32 v90, v90, v92
	ds_bpermute_b32 v92, v84, v90
	s_waitcnt lgkmcnt(2)
	v_add_f32_e32 v89, v89, v93
	ds_bpermute_b32 v93, v84, v89
	s_waitcnt lgkmcnt(2)
	v_add_f32_e32 v88, v88, v94
	ds_bpermute_b32 v94, v85, v88
	s_waitcnt lgkmcnt(2)
	v_add_f32_e32 v90, v90, v92
	ds_bpermute_b32 v92, v85, v90
	s_waitcnt lgkmcnt(2)
	v_add_f32_e32 v89, v89, v93
	ds_bpermute_b32 v93, v85, v89
	s_waitcnt lgkmcnt(2)
	v_add_f32_e32 v88, v88, v94
	ds_bpermute_b32 v94, v86, v88
	s_waitcnt lgkmcnt(2)
	v_add_f32_e32 v90, v90, v92
	ds_bpermute_b32 v92, v86, v90
	s_waitcnt lgkmcnt(2)
	v_add_f32_e32 v89, v89, v93
	ds_bpermute_b32 v93, v86, v89
	s_waitcnt lgkmcnt(2)
	v_add_f32_e32 v88, v88, v94
	ds_bpermute_b32 v94, v87, v88
	s_waitcnt lgkmcnt(2)
	v_add_f32_e32 v90, v90, v92
	ds_bpermute_b32 v92, v87, v90
	s_waitcnt lgkmcnt(2)
	v_add_f32_e32 v89, v89, v93
	ds_bpermute_b32 v93, v87, v89
	s_waitcnt lgkmcnt(2)
	v_add_f32_e32 v88, v88, v94
	v_fmamk_f32 v88, v88, 0x3a800000, v71
	v_mul_f32_e32 v94, 0x4f800000, v88
	v_cmp_gt_f32_e32 vcc, s3, v88
	s_waitcnt lgkmcnt(1)
	v_add_f32_e32 v90, v90, v92
	v_fmamk_f32 v90, v90, 0x3a800000, v71
	v_cndmask_b32_e32 v88, v88, v94, vcc
	v_sqrt_f32_e32 v92, v88
	s_waitcnt lgkmcnt(0)
	v_add_f32_e32 v89, v89, v93
	v_mul_f32_e32 v93, 0x4f800000, v90
	v_cmp_gt_f32_e64 s[4:5], s3, v90
	v_fmamk_f32 v89, v89, 0x3a800000, v71
	v_cmp_gt_f32_e64 s[6:7], s3, v89
	v_cndmask_b32_e64 v90, v90, v93, s[4:5]
	v_mul_f32_e32 v93, 0x4f800000, v89
	v_sqrt_f32_e32 v94, v90
	v_cndmask_b32_e64 v89, v89, v93, s[6:7]
	v_add_u32_e32 v95, -1, v92
	v_sqrt_f32_e32 v93, v89
	v_add_u32_e32 v96, 1, v92
	v_fma_f32 v97, -v95, v92, v88
	v_fma_f32 v98, -v96, v92, v88
	v_cmp_ge_f32_e64 s[8:9], 0, v97
	v_add_u32_e32 v97, 1, v94
	v_add_u32_e32 v99, -1, v93
	v_cndmask_b32_e64 v92, v92, v95, s[8:9]
	v_add_u32_e32 v95, -1, v94
	v_cmp_lt_f32_e64 s[8:9], 0, v98
	v_fma_f32 v98, -v97, v94, v90
	v_add_u32_e32 v100, 1, v93
	v_cndmask_b32_e64 v92, v92, v96, s[8:9]
	v_fma_f32 v96, -v95, v94, v90
	v_cmp_ge_f32_e64 s[8:9], 0, v96
	v_mul_f32_e32 v101, 0x37800000, v92
	v_fma_f32 v96, -v100, v93, v89
	v_cndmask_b32_e64 v94, v94, v95, s[8:9]
	v_cmp_lt_f32_e64 s[8:9], 0, v98
	v_fma_f32 v95, -v99, v93, v89
	v_cndmask_b32_e32 v92, v92, v101, vcc
	v_cndmask_b32_e64 v94, v94, v97, s[8:9]
	v_cmp_ge_f32_e32 vcc, 0, v95
	v_cmp_class_f32_e64 s[8:9], v88, v73
	s_nop 0
	v_cndmask_b32_e32 v93, v93, v99, vcc
	v_cmp_lt_f32_e32 vcc, 0, v96
	v_cndmask_b32_e64 v88, v92, v88, s[8:9]
	v_mul_f32_e32 v92, 0x37800000, v94
	v_cndmask_b32_e32 v93, v93, v100, vcc
	v_div_scale_f32 v95, s[8:9], v88, v88, 1.0
	v_cndmask_b32_e64 v92, v94, v92, s[4:5]
	v_cmp_class_f32_e64 s[4:5], v90, v73
	v_mul_f32_e32 v94, 0x37800000, v93
	v_rcp_f32_e32 v97, v95
	v_cndmask_b32_e64 v90, v92, v90, s[4:5]
	v_cndmask_b32_e64 v92, v93, v94, s[6:7]
	v_cmp_class_f32_e64 s[4:5], v89, v73
	v_div_scale_f32 v93, s[6:7], v90, v90, 1.0
	s_nop 0
	v_cndmask_b32_e64 v89, v92, v89, s[4:5]
	v_rcp_f32_e32 v92, v93
	v_div_scale_f32 v98, s[4:5], v89, v89, 1.0
	v_fma_f32 v101, -v95, v97, 1.0
	v_div_scale_f32 v96, vcc, 1.0, v88, 1.0
	v_rcp_f32_e32 v100, v98
	v_fmac_f32_e32 v97, v101, v97
	v_mul_f32_e32 v101, v96, v97
	v_fma_f32 v102, -v93, v92, 1.0
	v_div_scale_f32 v94, s[6:7], 1.0, v90, 1.0
	v_fma_f32 v103, -v95, v101, v96
	v_fmac_f32_e32 v92, v102, v92
	v_fmac_f32_e32 v101, v103, v97
	v_mul_f32_e32 v103, v94, v92
	v_fma_f32 v102, -v98, v100, 1.0
	v_fma_f32 v95, -v95, v101, v96
	v_fma_f32 v96, -v93, v103, v94
	v_div_scale_f32 v99, s[4:5], 1.0, v89, 1.0
	v_fmac_f32_e32 v100, v102, v100
	v_div_fmas_f32 v95, v95, v97, v101
	v_fmac_f32_e32 v103, v96, v92
	v_mul_f32_e32 v102, v99, v100
	v_div_fixup_f32 v88, v95, v88, 1.0
	v_fma_f32 v93, -v93, v103, v94
	s_mov_b64 vcc, s[6:7]
	v_fma_f32 v96, -v98, v102, v99
	v_mul_f32_e32 v14, v14, v88
	v_mul_f32_e32 v16, v16, v88
	v_mul_f32_e32 v94, v2, v88
	v_div_fmas_f32 v2, v93, v92, v103
	v_fmac_f32_e32 v102, v96, v100
	v_mul_f32_e32 v15, v15, v88
	v_mul_f32_e32 v17, v17, v88
	v_mul_f32_e32 v96, v4, v88
	v_mul_f32_e32 v4, v18, v14
	v_mul_f32_e32 v14, v20, v16
	v_div_fixup_f32 v2, v2, v90, 1.0
	v_mul_f32_e32 v10, v10, v88
	v_mul_f32_e32 v11, v11, v88
	v_mul_f32_e32 v12, v12, v88
	v_mul_f32_e32 v13, v13, v88
	v_mul_f32_e32 v6, v6, v88
	v_mul_f32_e32 v7, v7, v88
	v_mul_f32_e32 v8, v8, v88
	v_mul_f32_e32 v9, v9, v88
	v_mul_f32_e32 v95, v3, v88
	v_mul_f32_e32 v88, v5, v88
	v_fma_f32 v3, -v98, v102, v99
	v_mul_f32_e32 v5, v19, v15
	v_mul_f32_e32 v15, v21, v17
	s_mov_b64 vcc, s[4:5]
	v_mul_f32_e32 v16, v66, v2
	v_mul_f32_e32 v17, v67, v2
	v_mul_f32_e32 v18, v68, v2
	v_mul_f32_e32 v19, v69, v2
	v_mul_f32_e32 v20, v62, v2
	v_mul_f32_e32 v21, v63, v2
	v_mul_f32_e32 v62, v64, v2
; #define GAS __attribute__((address_space(1)))
; __device__ __forceinline__ unsigned f2bf(float f) { unsigned u = __builtin_bit_cast(unsigned, f); return (u + 0x7fffu + ((u >> 16) & 1u)) >> 16; }
; __device__ __forceinline__ unsigned pk2(float lo, float hi) { return f2bf(lo) | (f2bf(hi) << 16); }
; __device__ __forceinline__ void rms_rows4_to_bf16(const float* xrow, const float* g, bf16* orow, int lane) {
;     ...
;     for (int r = 0; r < 4; ++r) { const float rs = 1.f / sqrtf(wave_sum(s[r], lane) * (1.f / D) + RMS_EPS);
;         GAS unsigned long long* o8 = (GAS unsigned long long*)(orow + (size_t)r * D) + lane;
; #pragma unroll
;         for (int j = 0; j < 4; ++j) { const f32x4 gg = gr[64 * j];
;             o8[64 * j] = (unsigned long long)pk2(v[r][j].x * rs * gg.x, v[r][j].y * rs * gg.y) | ((unsigned long long)pk2(v[r][j].z * rs * gg.z, v[r][j].w * rs * gg.w) << 32); } }
	v_mul_f32_e32 v63, v65, v2
	v_mul_f32_e32 v58, v58, v2
	v_mul_f32_e32 v59, v59, v2
	v_mul_f32_e32 v60, v60, v2
	v_mul_f32_e32 v61, v61, v2
	v_mul_f32_e32 v54, v54, v2
	v_mul_f32_e32 v55, v55, v2
	v_mul_f32_e32 v56, v56, v2
	v_mul_f32_e32 v57, v57, v2
	v_bfe_u32 v2, v4, 16, 1
	v_bfe_u32 v65, v14, 16, 1
	v_div_fmas_f32 v3, v3, v100, v102
	v_bfe_u32 v64, v5, 16, 1
	v_bfe_u32 v66, v15, 16, 1
	v_add3_u32 v2, v4, v2, s13
	v_add3_u32 v4, v14, v65, s13
	v_div_fixup_f32 v67, v3, v89, 1.0
	v_add3_u32 v3, v5, v64, s13
	v_add3_u32 v5, v15, v66, s13
	v_lshrrev_b32_e32 v2, 16, v2
	v_lshrrev_b32_e32 v4, 16, v4
	v_and_or_b32 v2, v3, s15, v2
	v_and_or_b32 v3, v5, s15, v4
	global_store_dwordx2 v[78:79], v[2:3], off
	v_mov_b32_e32 v2, v116
	v_mov_b32_e32 v3, v117
	v_mov_b32_e32 v4, v118
	v_mov_b32_e32 v5, v119
	v_mul_f32_e32 v14, v50, v67
	v_mul_f32_e32 v50, v52, v67
	v_mul_f32_e32 v15, v51, v67
	v_mul_f32_e32 v51, v53, v67
	v_mul_f32_e32 v46, v46, v67
	v_mul_f32_e32 v47, v47, v67
	v_mul_f32_e32 v2, v2, v10
	v_mul_f32_e32 v4, v4, v12
	v_mul_f32_e32 v3, v3, v11
	v_mul_f32_e32 v5, v5, v13
	v_bfe_u32 v10, v2, 16, 1
	v_bfe_u32 v12, v4, 16, 1
	v_bfe_u32 v11, v3, 16, 1
	v_bfe_u32 v13, v5, 16, 1
	v_add3_u32 v2, v2, v10, s13
	v_add3_u32 v4, v4, v12, s13
	v_add3_u32 v3, v3, v11, s13
	v_add3_u32 v5, v5, v13, s13
	v_lshrrev_b32_e32 v2, 16, v2
	v_lshrrev_b32_e32 v4, 16, v4
	v_and_or_b32 v2, v3, s15, v2
	v_and_or_b32 v3, v5, s15, v4
	global_store_dwordx2 v[78:79], v[2:3], off offset:512
	v_mov_b32_e32 v2, v120
	v_mov_b32_e32 v3, v121
	v_mov_b32_e32 v4, v122
	v_mov_b32_e32 v5, v123
	v_mul_f32_e32 v10, v45, v67
	v_mul_f32_e32 v2, v2, v6
	v_mul_f32_e32 v4, v4, v8
	v_mul_f32_e32 v3, v3, v7
	v_mul_f32_e32 v5, v5, v9
	v_bfe_u32 v6, v2, 16, 1
	v_bfe_u32 v8, v4, 16, 1
	v_bfe_u32 v7, v3, 16, 1
	v_bfe_u32 v9, v5, 16, 1
	v_add3_u32 v2, v2, v6, s13
	v_add3_u32 v4, v4, v8, s13
	v_add3_u32 v3, v3, v7, s13
	v_add3_u32 v5, v5, v9, s13
	v_lshrrev_b32_e32 v2, 16, v2
	v_lshrrev_b32_e32 v4, 16, v4
	v_and_or_b32 v2, v3, s15, v2
	v_and_or_b32 v3, v5, s15, v4
	global_store_dwordx2 v[78:79], v[2:3], off offset:1024
	v_mov_b32_e32 v2, v124
	v_mov_b32_e32 v3, v125
	v_mov_b32_e32 v4, v126
	v_mov_b32_e32 v5, v127
	v_mul_f32_e32 v2, v94, v2
	v_mul_f32_e32 v4, v96, v4
	v_mul_f32_e32 v3, v95, v3
	v_mul_f32_e32 v5, v88, v5
	v_bfe_u32 v6, v2, 16, 1
	v_bfe_u32 v8, v4, 16, 1
	v_bfe_u32 v7, v3, 16, 1
	v_bfe_u32 v9, v5, 16, 1
	v_add3_u32 v2, v2, v6, s13
	v_add3_u32 v4, v4, v8, s13
	v_add3_u32 v3, v3, v7, s13
	v_add3_u32 v5, v5, v9, s13
	v_lshrrev_b32_e32 v2, 16, v2
	v_lshrrev_b32_e32 v4, 16, v4
	v_and_or_b32 v2, v3, s15, v2
	v_and_or_b32 v3, v5, s15, v4
	global_store_dwordx2 v[78:79], v[2:3], off offset:1536
	v_mov_b32_e32 v2, v112
	v_mov_b32_e32 v3, v113
	v_mov_b32_e32 v4, v114
	v_mov_b32_e32 v5, v115
	v_mul_f32_e32 v2, v2, v16
	v_mul_f32_e32 v4, v4, v18
	v_mul_f32_e32 v3, v3, v17
	v_mul_f32_e32 v5, v5, v19
	v_bfe_u32 v6, v2, 16, 1
	v_bfe_u32 v8, v4, 16, 1
	v_bfe_u32 v7, v3, 16, 1
	v_bfe_u32 v9, v5, 16, 1
	v_add3_u32 v2, v2, v6, s13
	v_add3_u32 v4, v4, v8, s13
	v_add3_u32 v3, v3, v7, s13
	v_add3_u32 v5, v5, v9, s13
	v_lshrrev_b32_e32 v2, 16, v2
	v_lshrrev_b32_e32 v4, 16, v4
	v_and_or_b32 v2, v3, s15, v2
	v_and_or_b32 v3, v5, s15, v4
	global_store_dwordx2 v[78:79], v[2:3], off offset:2048
	v_mov_b32_e32 v2, v116
	v_mov_b32_e32 v3, v117
	v_mov_b32_e32 v4, v118
	v_mov_b32_e32 v5, v119
	v_mul_f32_e32 v2, v2, v20
	v_mul_f32_e32 v4, v4, v62
	v_mul_f32_e32 v3, v3, v21
	v_mul_f32_e32 v5, v5, v63
	v_bfe_u32 v6, v2, 16, 1
	v_bfe_u32 v8, v4, 16, 1
	v_bfe_u32 v7, v3, 16, 1
	v_bfe_u32 v9, v5, 16, 1
	v_add3_u32 v2, v2, v6, s13
	v_add3_u32 v4, v4, v8, s13
	v_add3_u32 v3, v3, v7, s13
	v_add3_u32 v5, v5, v9, s13
	v_lshrrev_b32_e32 v2, 16, v2
	v_lshrrev_b32_e32 v4, 16, v4
	v_and_or_b32 v2, v3, s15, v2
	v_and_or_b32 v3, v5, s15, v4
	global_store_dwordx2 v[78:79], v[2:3], off offset:2560
	v_mov_b32_e32 v2, v120
	v_mov_b32_e32 v3, v121
	v_mov_b32_e32 v4, v122
	v_mov_b32_e32 v5, v123
	v_mul_f32_e32 v2, v2, v58
	v_mul_f32_e32 v4, v4, v60
	v_mul_f32_e32 v3, v3, v59
	v_mul_f32_e32 v5, v5, v61
	v_bfe_u32 v6, v2, 16, 1
	v_bfe_u32 v8, v4, 16, 1
	v_bfe_u32 v7, v3, 16, 1
	v_bfe_u32 v9, v5, 16, 1
	v_add3_u32 v2, v2, v6, s13
	v_add3_u32 v4, v4, v8, s13
	v_add3_u32 v3, v3, v7, s13
	v_add3_u32 v5, v5, v9, s13
	v_lshrrev_b32_e32 v2, 16, v2
	v_lshrrev_b32_e32 v4, 16, v4
	v_and_or_b32 v2, v3, s15, v2
	v_and_or_b32 v3, v5, s15, v4
	global_store_dwordx2 v[78:79], v[2:3], off offset:3072
	v_mov_b32_e32 v2, v124
	v_mov_b32_e32 v3, v125
	v_mov_b32_e32 v4, v126
	v_mov_b32_e32 v5, v127
	v_mul_f32_e32 v2, v54, v2
	v_mul_f32_e32 v4, v56, v4
	v_mul_f32_e32 v3, v55, v3
	v_mul_f32_e32 v5, v57, v5
	v_bfe_u32 v6, v2, 16, 1
	v_bfe_u32 v8, v4, 16, 1
	v_bfe_u32 v7, v3, 16, 1
	v_bfe_u32 v9, v5, 16, 1
	v_add3_u32 v2, v2, v6, s13
	v_add3_u32 v4, v4, v8, s13
	v_add3_u32 v3, v3, v7, s13
	v_add3_u32 v5, v5, v9, s13
	v_lshrrev_b32_e32 v2, 16, v2
	v_lshrrev_b32_e32 v4, 16, v4
	v_and_or_b32 v2, v3, s15, v2
	v_and_or_b32 v3, v5, s15, v4
	global_store_dwordx2 v[78:79], v[2:3], off offset:3584
	v_mov_b32_e32 v2, v112
	v_mov_b32_e32 v3, v113
	v_mov_b32_e32 v4, v114
	v_mov_b32_e32 v5, v115
	v_lshl_add_u64 v[78:79], v[78:79], 0, s[28:29]
	v_mul_f32_e32 v2, v2, v14
	v_mul_f32_e32 v4, v4, v50
	v_mul_f32_e32 v3, v3, v15
	v_mul_f32_e32 v5, v5, v51
	v_bfe_u32 v6, v2, 16, 1
	v_bfe_u32 v8, v4, 16, 1
	v_bfe_u32 v7, v3, 16, 1
	v_bfe_u32 v9, v5, 16, 1
	v_add3_u32 v2, v2, v6, s13
	v_add3_u32 v4, v4, v8, s13
	v_add3_u32 v3, v3, v7, s13
	v_add3_u32 v5, v5, v9, s13
	v_lshrrev_b32_e32 v2, 16, v2
	v_lshrrev_b32_e32 v4, 16, v4
	v_and_or_b32 v2, v3, s15, v2
	v_and_or_b32 v3, v5, s15, v4
	global_store_dwordx2 v[80:81], v[2:3], off
	v_mov_b32_e32 v2, v116
	v_mov_b32_e32 v3, v117
	v_mov_b32_e32 v4, v118
	v_mov_b32_e32 v5, v119
	v_mul_f32_e32 v6, v48, v67
	v_mul_f32_e32 v7, v49, v67
	v_mul_f32_e32 v2, v2, v46
	v_mul_f32_e32 v4, v4, v6
	v_mul_f32_e32 v3, v3, v47
	v_mul_f32_e32 v5, v5, v7
	v_bfe_u32 v6, v2, 16, 1
	v_bfe_u32 v8, v4, 16, 1
	v_bfe_u32 v7, v3, 16, 1
	v_bfe_u32 v9, v5, 16, 1
	v_add3_u32 v2, v2, v6, s13
	v_add3_u32 v4, v4, v8, s13
	v_add3_u32 v3, v3, v7, s13
	v_add3_u32 v5, v5, v9, s13
	v_lshrrev_b32_e32 v2, 16, v2
	v_lshrrev_b32_e32 v4, 16, v4
	v_and_or_b32 v2, v3, s15, v2
	v_and_or_b32 v3, v5, s15, v4
	global_store_dwordx2 v[80:81], v[2:3], off offset:512
	v_mov_b32_e32 v2, v120
	v_mov_b32_e32 v3, v121
	v_mov_b32_e32 v4, v122
	v_mov_b32_e32 v5, v123
	ds_bpermute_b32 v6, v83, v91
	v_mul_f32_e32 v9, v44, v67
	v_mul_f32_e32 v8, v43, v67
	s_waitcnt lgkmcnt(0)
; #define GAS __attribute__((address_space(1)))
; __device__ __forceinline__ unsigned pk2(float lo, float hi) { return f2bf(lo) | (f2bf(hi) << 16); }
; __device__ __forceinline__ void rms_rows4_to_bf16(const float* xrow, const float* g, bf16* orow, int lane) {
;     ...
;     for (int r = 0; r < 4; ++r) { const float rs = 1.f / sqrtf(wave_sum(s[r], lane) * (1.f / D) + RMS_EPS);
;         GAS unsigned long long* o8 = (GAS unsigned long long*)(orow + (size_t)r * D) + lane;
; #pragma unroll
;         for (int j = 0; j < 4; ++j) { const f32x4 gg = gr[64 * j];
;             o8[64 * j] = (unsigned long long)pk2(v[r][j].x * rs * gg.x, v[r][j].y * rs * gg.y) | ((unsigned long long)pk2(v[r][j].z * rs * gg.z, v[r][j].w * rs * gg.w) << 32); } }
	v_add_f32_e32 v6, v91, v6
	ds_bpermute_b32 v7, v84, v6
	s_waitcnt lgkmcnt(0)
	v_add_f32_e32 v6, v6, v7
	v_mul_f32_e32 v7, v42, v67
	v_mul_f32_e32 v2, v2, v7
	v_mul_f32_e32 v4, v4, v9
	v_mul_f32_e32 v3, v3, v8
	v_mul_f32_e32 v5, v5, v10
	v_bfe_u32 v7, v2, 16, 1
	v_bfe_u32 v9, v4, 16, 1
	v_bfe_u32 v8, v3, 16, 1
	v_bfe_u32 v10, v5, 16, 1
	v_add3_u32 v2, v2, v7, s13
	v_add3_u32 v4, v4, v9, s13
	v_add3_u32 v3, v3, v8, s13
	v_add3_u32 v5, v5, v10, s13
	v_lshrrev_b32_e32 v2, 16, v2
	v_lshrrev_b32_e32 v4, 16, v4
	v_and_or_b32 v2, v3, s15, v2
	v_and_or_b32 v3, v5, s15, v4
	global_store_dwordx2 v[80:81], v[2:3], off offset:1024
	v_mov_b32_e32 v2, v124
	v_mov_b32_e32 v3, v125
	v_mov_b32_e32 v4, v126
	v_mov_b32_e32 v5, v127
	ds_bpermute_b32 v7, v85, v6
	v_mul_f32_e32 v9, v40, v67
	v_mul_f32_e32 v8, v39, v67
	v_mul_f32_e32 v10, v41, v67
	s_waitcnt lgkmcnt(0)
	v_add_f32_e32 v6, v6, v7
	ds_bpermute_b32 v7, v86, v6
	s_waitcnt lgkmcnt(0)
	v_add_f32_e32 v6, v6, v7
	ds_bpermute_b32 v7, v87, v6
	s_waitcnt lgkmcnt(0)
	v_add_f32_e32 v6, v6, v7
	v_fmamk_f32 v6, v6, 0x3a800000, v71
	v_mul_f32_e32 v7, 0x4f800000, v6
	v_cmp_gt_f32_e32 vcc, s3, v6
	v_mul_f32_e32 v4, v9, v4
	v_cndmask_b32_e32 v6, v6, v7, vcc
	v_mul_f32_e32 v7, v38, v67
	v_mul_f32_e32 v2, v7, v2
	v_mul_f32_e32 v3, v8, v3
	v_mul_f32_e32 v5, v10, v5
	v_bfe_u32 v7, v2, 16, 1
	v_bfe_u32 v9, v4, 16, 1
	v_bfe_u32 v8, v3, 16, 1
	v_bfe_u32 v10, v5, 16, 1
	v_add3_u32 v2, v2, v7, s13
	v_add3_u32 v4, v4, v9, s13
	v_add3_u32 v3, v3, v8, s13
	v_add3_u32 v5, v5, v10, s13
	v_lshrrev_b32_e32 v2, 16, v2
	v_lshrrev_b32_e32 v4, 16, v4
	v_and_or_b32 v2, v3, s15, v2
	v_and_or_b32 v3, v5, s15, v4
	global_store_dwordx2 v[80:81], v[2:3], off offset:1536
	v_mov_b32_e32 v2, v112
	v_mov_b32_e32 v3, v113
	v_mov_b32_e32 v4, v114
	v_mov_b32_e32 v5, v115
	v_sqrt_f32_e32 v7, v6
	s_nop 0
	v_add_u32_e32 v8, -1, v7
	v_add_u32_e32 v9, 1, v7
	v_fma_f32 v10, -v8, v7, v6
	v_fma_f32 v11, -v9, v7, v6
	v_cmp_ge_f32_e64 s[4:5], 0, v10
	s_nop 1
	v_cndmask_b32_e64 v7, v7, v8, s[4:5]
	v_cmp_lt_f32_e64 s[4:5], 0, v11
	s_nop 1
	v_cndmask_b32_e64 v7, v7, v9, s[4:5]
	v_mul_f32_e32 v8, 0x37800000, v7
	v_cndmask_b32_e32 v7, v7, v8, vcc
	v_cmp_class_f32_e32 vcc, v6, v73
	s_nop 1
	v_cndmask_b32_e32 v6, v7, v6, vcc
	v_div_scale_f32 v7, s[4:5], v6, v6, 1.0
	v_rcp_f32_e32 v9, v7
	v_div_scale_f32 v8, vcc, 1.0, v6, 1.0
	v_fma_f32 v10, -v7, v9, 1.0
	v_fmac_f32_e32 v9, v10, v9
	v_mul_f32_e32 v10, v8, v9
	v_fma_f32 v11, -v7, v10, v8
	v_fmac_f32_e32 v10, v11, v9
	v_fma_f32 v7, -v7, v10, v8
	v_div_fmas_f32 v7, v7, v9, v10
	v_div_fixup_f32 v6, v7, v6, 1.0
	v_mul_f32_e32 v7, v34, v6
	v_mul_f32_e32 v9, v36, v6
	v_mul_f32_e32 v8, v35, v6
	v_mul_f32_e32 v10, v37, v6
	v_mul_f32_e32 v2, v2, v7
	v_mul_f32_e32 v4, v4, v9
	v_mul_f32_e32 v3, v3, v8
	v_mul_f32_e32 v5, v5, v10
	v_bfe_u32 v7, v2, 16, 1
	v_bfe_u32 v9, v4, 16, 1
	v_bfe_u32 v8, v3, 16, 1
	v_bfe_u32 v10, v5, 16, 1
	v_add3_u32 v2, v2, v7, s13
	v_add3_u32 v4, v4, v9, s13
	v_add3_u32 v3, v3, v8, s13
	v_add3_u32 v5, v5, v10, s13
	v_lshrrev_b32_e32 v2, 16, v2
	v_lshrrev_b32_e32 v4, 16, v4
	v_and_or_b32 v2, v3, s15, v2
	v_and_or_b32 v3, v5, s15, v4
	global_store_dwordx2 v[80:81], v[2:3], off offset:2048
	v_mov_b32_e32 v2, v116
	v_mov_b32_e32 v3, v117
	v_mov_b32_e32 v4, v118
	v_mov_b32_e32 v5, v119
	v_mul_f32_e32 v7, v30, v6
	v_mul_f32_e32 v9, v32, v6
	v_mul_f32_e32 v8, v31, v6
	v_mul_f32_e32 v10, v33, v6
	v_mul_f32_e32 v2, v2, v7
	v_mul_f32_e32 v4, v4, v9
	v_mul_f32_e32 v3, v3, v8
	v_mul_f32_e32 v5, v5, v10
	v_bfe_u32 v7, v2, 16, 1
	v_bfe_u32 v9, v4, 16, 1
	v_bfe_u32 v8, v3, 16, 1
	v_bfe_u32 v10, v5, 16, 1
	v_add3_u32 v2, v2, v7, s13
	v_add3_u32 v4, v4, v9, s13
	v_add3_u32 v3, v3, v8, s13
	v_add3_u32 v5, v5, v10, s13
	v_lshrrev_b32_e32 v2, 16, v2
	v_lshrrev_b32_e32 v4, 16, v4
	v_and_or_b32 v2, v3, s15, v2
	v_and_or_b32 v3, v5, s15, v4
	global_store_dwordx2 v[80:81], v[2:3], off offset:2560
	v_mov_b32_e32 v2, v120
	v_mov_b32_e32 v3, v121
	v_mov_b32_e32 v4, v122
	v_mov_b32_e32 v5, v123
	v_mul_f32_e32 v7, v26, v6
	v_mul_f32_e32 v9, v28, v6
	v_mul_f32_e32 v8, v27, v6
	v_mul_f32_e32 v10, v29, v6
	v_mul_f32_e32 v2, v2, v7
	v_mul_f32_e32 v4, v4, v9
	v_mul_f32_e32 v3, v3, v8
	v_mul_f32_e32 v5, v5, v10
	v_bfe_u32 v7, v2, 16, 1
	v_bfe_u32 v9, v4, 16, 1
	v_bfe_u32 v8, v3, 16, 1
	v_bfe_u32 v10, v5, 16, 1
	v_add3_u32 v2, v2, v7, s13
	v_add3_u32 v4, v4, v9, s13
	v_add3_u32 v3, v3, v8, s13
	v_add3_u32 v5, v5, v10, s13
	v_lshrrev_b32_e32 v2, 16, v2
	v_lshrrev_b32_e32 v4, 16, v4
	v_and_or_b32 v2, v3, s15, v2
	v_and_or_b32 v3, v5, s15, v4
	global_store_dwordx2 v[80:81], v[2:3], off offset:3072
	v_mov_b32_e32 v2, v124
	v_mov_b32_e32 v3, v125
	v_mov_b32_e32 v4, v126
	v_mov_b32_e32 v5, v127
	v_mul_f32_e32 v7, v22, v6
	v_mul_f32_e32 v9, v24, v6
	v_mul_f32_e32 v8, v23, v6
	v_mul_f32_e32 v6, v25, v6
	v_mul_f32_e32 v2, v7, v2
	v_mul_f32_e32 v4, v9, v4
	v_mul_f32_e32 v3, v8, v3
	v_mul_f32_e32 v5, v6, v5
	v_bfe_u32 v6, v2, 16, 1
	v_bfe_u32 v8, v4, 16, 1
	v_bfe_u32 v7, v3, 16, 1
	v_bfe_u32 v9, v5, 16, 1
	v_add3_u32 v2, v2, v6, s13
	v_add3_u32 v4, v4, v8, s13
	v_add3_u32 v3, v3, v7, s13
	v_add3_u32 v5, v5, v9, s13
	v_lshrrev_b32_e32 v2, 16, v2
	v_lshrrev_b32_e32 v4, 16, v4
	v_and_or_b32 v2, v3, s15, v2
	v_and_or_b32 v3, v5, s15, v4
	global_store_dwordx2 v[80:81], v[2:3], off offset:3584
	s_cbranch_scc0 .LBB0_59
